# kernel-wide static s_setprio 1 for waves 4-7 (second-dispatched half), no per-phase priority flips
# baseline (speedup 1.0000x reference)
; #define LAS __attribute__((address_space(3)))
; __global__ void __launch_bounds__(NWAVES * 64, 2) fwd_megakernel(Params P) {
;     extern __shared__ __attribute__((aligned(16))) unsigned char lds_raw[];
;     cg::grid_group grid = cg::this_grid();
;     LAS unsigned char* lds = (LAS unsigned char*)lds_raw;
;     const int tid = threadIdx.x, lane = tid & 63, wave = __builtin_amdgcn_readfirstlane(tid >> 6);
;     const int G = gridDim.x, bx = blockIdx.x;
;     const int vcu = (G % 8 == 0) ? (bx % 8) * (G / 8) + bx / 8 : bx;
_Z14fwd_megakernel6Params:
	s_load_dwordx2 s[36:37], s[0:1], 0xc8
	s_mov_b64 s[38:39], s[0:1]
	s_add_u32 s4, s38, 0xc8
	s_addc_u32 s5, s39, 0
	v_and_b32_e32 v236, 0x3ff, v0
	s_waitcnt lgkmcnt(0)
	s_and_b32 s0, s36, 7
	v_readfirstlane_b32 s12, v236
	s_nop 3
	s_cmp_lt_u32 s12, 0x100
	s_cbranch_scc1 .Lsp_skip
	s_setprio 1
.Lsp_skip:
	s_cmp_lg_u32 s0, 0
	s_mov_b32 s13, s2
	s_cbranch_scc1 .LBB0_1
	s_getpc_b64 s[98:99]
